# 256x256 GEMM phase prologues (all 13 instances): second batch of LDS-DMA stage loads issued before the first wait+barrier (counted vmcnt(8)), so both cold load batches are in flight together
# baseline (speedup 1.0000x reference)
; #define PG8_STAGE(bufoff, gbase, voff) do { _Pragma("unroll") for (int _i = 0; _i < 2; ++_i) \
;         __builtin_amdgcn_global_load_lds((const unsigned*)((const char*)(gbase) + (voff)[_i]), (PG8_LAS unsigned*)(lds + (bufoff) + ldsw + _i * 8192), 16, 0, 0); } while (0)
; #define PG8_WAIT_V(n) asm volatile("s_waitcnt vmcnt(" #n ")" ::: "memory")
; #define PG8_BAR __builtin_amdgcn_s_barrier()
; template <class Epi, class Sched, bool ALIGN_EPI = false, bool SP2 = false, bool NAT = false>
; __device__ __forceinline__ void gemm_phase(PG8_LAS unsigned char* lds, const Gemm g, const Sched& S, const Epi& E) {
;     ...
;     for (int i = 0; i < 2; ++i) { int R, C; stage_rc(tid * 16 + i * 8192, R, C); const int Rb = Epi::PERM ? ((R & ~31) + perm32(R & 31)) : R;
;         voffA[i] = (unsigned)(R * K + C) * 2u; voffB[i] = (unsigned)(Rb * K + C) * 2u; }
;     const size_t kstep = (size_t)(BK * 2);
;     const size_t hstep = (size_t)HALF * K * 2;
;     const size_t tstep = 2 * hstep;
;     const unsigned ldsw = (unsigned)wid * 1024u;
;     const int aoff = lds_byte(wr * 64 + fr, fq * 8), boff = lds_byte(wc * 32 + fr, fq * 8);
;     ...
;     if constexpr (SP2) {
;         PG8_STAGE(PG8_SB(0, 0), cB, voffB); PG8_STAGE(PG8_SB(0, 1), cB + hstep, voffB); PG8_STAGE(PG8_SA(0, 0), cA, voffA); PG8_STAGE(PG8_SA(0, 1), cA + hstep, voffA);
;         if (wr == 1) PG8_BAR;
;         PG8_WAIT_V(2); PG8_BAR;
;         PG8_STAGE(PG8_SB(1, 0), cB + kstep, voffB); PG8_STAGE(PG8_SA(1, 0), cA + kstep, voffA); PG8_STAGE(PG8_SB(1, 1), cB + hstep + kstep, voffB);
;         PG8_WAIT_V(6); PG8_BAR;
.LBB0_140:
	s_lshl_b32 s4, s16, 5
	s_and_b32 s16, s4, 0x60
	s_add_i32 m0, s31, 0x18000
	v_lshl_add_u64 v[10:11], v[10:11], 0, s[92:93]
	s_lshl_b32 s17, s15, 13
	s_lshl_b32 s18, s16, 7
	global_load_lds_dwordx4 v[10:11], off
	v_lshl_add_u64 v[8:9], v[8:9], 0, s[92:93]
	s_add_i32 m0, s31, 0x1a000
	s_add_i32 s36, s31, 0x8000
	s_add_i32 s37, s31, 0xa000
	global_load_lds_dwordx4 v[8:9], off
	v_lshl_add_u64 v[4:5], v[4:5], 0, s[92:93]
	s_mov_b32 m0, s36
	s_add_u32 s4, s24, 0x40080
	global_load_lds_dwordx4 v[4:5], off
	v_lshl_add_u64 v[4:5], v[6:7], 0, s[92:93]
	s_mov_b32 m0, s37
	s_addc_u32 s5, s25, 0
	global_load_lds_dwordx4 v[4:5], off
	s_add_i32 m0, s31, 0x1c000
	v_lshl_add_u64 v[4:5], s[4:5], 0, v[132:133]
	global_load_lds_dwordx4 v[4:5], off
	v_lshl_add_u64 v[4:5], s[4:5], 0, v[0:1]
	s_add_i32 m0, s31, 0x1e000
	s_cmpk_lt_u32 s14, 0x100
	global_load_lds_dwordx4 v[4:5], off
	v_bfe_u32 v5, v2, 4, 2
	v_and_b32_e32 v4, 15, v2
	v_lshlrev_b32_e32 v6, 4, v5
	v_lshlrev_b32_e32 v2, 2, v2
	v_lshl_or_b32 v158, s15, 6, v4
	v_lshl_or_b32 v4, v4, 6, v6
	v_and_b32_e32 v2, 32, v2
	v_bitop3_b32 v6, v4, s17, v2 bitop3:0xde
	v_bitop3_b32 v159, v4, s18, v2 bitop3:0xde
	v_lshlrev_b32_e32 v4, 14, v12
	v_and_b32_e32 v4, 0xffff8000, v4
	v_lshlrev_b32_e32 v2, 2, v5
	v_lshl_add_u32 v4, v13, 11, v4
	v_and_b32_e32 v5, 1, v12
	v_lshl_or_b32 v4, v5, 6, v4
	v_lshl_add_u32 v134, v14, 1, v4
	v_lshlrev_b32_e32 v4, 14, v15
	v_and_b32_e32 v4, 0xffff8000, v4
	s_waitcnt vmcnt(8)
	s_barrier
	s_waitcnt vmcnt(6)
	v_lshl_add_u32 v4, v16, 11, v4
	v_and_b32_e32 v5, 1, v15
	v_lshl_or_b32 v4, v5, 6, v4
	v_readlane_b32 s4, v254, 7
	s_cselect_b64 s[14:15], -1, 0
	v_mov_b32_e32 v135, v3
	v_lshl_add_u32 v136, v17, 1, v4
	v_mov_b32_e32 v137, v3
	s_mov_b32 s38, 0
	v_add_u32_e32 v160, 0, v6
	s_lshl_b32 s39, s16, 1
	v_lshlrev_b32_e32 v2, 1, v2
	v_readlane_b32 s43, v254, 6
	s_mov_b32 s42, s4
	s_barrier
	v_readlane_b32 s5, v254, 8
	s_branch .LBB0_143

; #define PG8_STAGE(bufoff, gbase, voff) do { _Pragma("unroll") for (int _i = 0; _i < 2; ++_i) \
;         __builtin_amdgcn_global_load_lds((const unsigned*)((const char*)(gbase) + (voff)[_i]), (PG8_LAS unsigned*)(lds + (bufoff) + ldsw + _i * 8192), 16, 0, 0); } while (0)
; #define PG8_WAIT_V(n) asm volatile("s_waitcnt vmcnt(" #n ")" ::: "memory")
; #define PG8_BAR __builtin_amdgcn_s_barrier()
; template <class Epi, class Sched, bool ALIGN_EPI = false, bool SP2 = false, bool NAT = false>
; __device__ __forceinline__ void gemm_phase(PG8_LAS unsigned char* lds, const Gemm g, const Sched& S, const Epi& E) {
;     ...
;     for (int i = 0; i < 2; ++i) { int R, C; stage_rc(tid * 16 + i * 8192, R, C); const int Rb = Epi::PERM ? ((R & ~31) + perm32(R & 31)) : R;
;         voffA[i] = (unsigned)(R * K + C) * 2u; voffB[i] = (unsigned)(Rb * K + C) * 2u; }
;     const size_t kstep = (size_t)(BK * 2);
;     const size_t hstep = (size_t)HALF * K * 2;
;     const size_t tstep = 2 * hstep;
;     const unsigned ldsw = (unsigned)wid * 1024u;
;     const int aoff = lds_byte(wr * 64 + fr, fq * 8), boff = lds_byte(wc * 32 + fr, fq * 8);
;     ...
;     if constexpr (SP2) {
;         PG8_STAGE(PG8_SB(0, 0), cB, voffB); PG8_STAGE(PG8_SB(0, 1), cB + hstep, voffB); PG8_STAGE(PG8_SA(0, 0), cA, voffA); PG8_STAGE(PG8_SA(0, 1), cA + hstep, voffA);
;         if (wr == 1) PG8_BAR;
;         PG8_WAIT_V(2); PG8_BAR;
;         PG8_STAGE(PG8_SB(1, 0), cB + kstep, voffB); PG8_STAGE(PG8_SA(1, 0), cA + kstep, voffA); PG8_STAGE(PG8_SB(1, 1), cB + hstep + kstep, voffB);
;         PG8_WAIT_V(6); PG8_BAR;
.LBB0_158:
	s_lshl_b32 s6, s6, 5
	s_and_b32 s36, s6, 0x60
	s_add_i32 m0, s30, 0x18000
	v_lshl_add_u64 v[10:11], v[10:11], 0, s[92:93]
	s_lshl_b32 s18, s5, 13
	s_lshl_b32 s19, s36, 7
	global_load_lds_dwordx4 v[10:11], off
	v_lshl_add_u64 v[8:9], v[8:9], 0, s[92:93]
	s_add_i32 m0, s30, 0x1a000
	s_add_i32 s37, s30, 0x8000
	s_add_i32 s39, s30, 0xa000
	global_load_lds_dwordx4 v[8:9], off
	v_lshl_add_u64 v[4:5], v[4:5], 0, s[92:93]
	s_mov_b32 m0, s37
	s_add_u32 s6, s26, 0x18080
	global_load_lds_dwordx4 v[4:5], off
	v_lshl_add_u64 v[4:5], v[6:7], 0, s[92:93]
	s_mov_b32 m0, s39
	s_addc_u32 s7, s27, 0
	global_load_lds_dwordx4 v[4:5], off
	s_add_i32 m0, s30, 0x1c000
	v_lshl_add_u64 v[4:5], s[6:7], 0, v[132:133]
	global_load_lds_dwordx4 v[4:5], off
	v_lshl_add_u64 v[4:5], s[6:7], 0, v[0:1]
	s_add_i32 m0, s30, 0x1e000
	s_cmpk_lt_u32 s4, 0x100
	global_load_lds_dwordx4 v[4:5], off
	v_bfe_u32 v5, v2, 4, 2
	v_and_b32_e32 v4, 15, v2
	v_lshlrev_b32_e32 v6, 4, v5
	v_lshlrev_b32_e32 v2, 2, v2
	v_lshl_or_b32 v137, s5, 6, v4
	v_lshl_or_b32 v4, v4, 6, v6
	v_and_b32_e32 v2, 32, v2
	v_bitop3_b32 v6, v4, s18, v2 bitop3:0xde
	v_bitop3_b32 v161, v4, s19, v2 bitop3:0xde
	s_cselect_b64 s[18:19], -1, 0
	s_lshl_b32 s4, s36, 1
	s_waitcnt vmcnt(8)
	s_barrier
	s_waitcnt vmcnt(6)
	s_waitcnt lgkmcnt(0)
	s_add_u32 s4, s10, s4
	v_lshlrev_b32_e32 v134, 3, v5
	s_addc_u32 s5, s11, 0
	v_mov_b32_e32 v135, v3
	v_readlane_b32 s10, v254, 59
	v_add_u32_e32 v162, 0, v6
	v_lshlrev_b32_e32 v136, 2, v5
	v_lshl_add_u64 v[154:155], s[4:5], 0, v[134:135]
	v_readlane_b32 s11, v254, 60
	v_readlane_b32 s33, v254, 36
	v_readlane_b32 s44, v254, 33
	s_barrier
	s_branch .LBB0_161

; #define PG8_STAGE(bufoff, gbase, voff) do { _Pragma("unroll") for (int _i = 0; _i < 2; ++_i) \
;         __builtin_amdgcn_global_load_lds((const unsigned*)((const char*)(gbase) + (voff)[_i]), (PG8_LAS unsigned*)(lds + (bufoff) + ldsw + _i * 8192), 16, 0, 0); } while (0)
; #define PG8_WAIT_V(n) asm volatile("s_waitcnt vmcnt(" #n ")" ::: "memory")
; #define PG8_BAR __builtin_amdgcn_s_barrier()
; template <class Epi, class Sched, bool ALIGN_EPI = false, bool SP2 = false, bool NAT = false>
; __device__ __forceinline__ void gemm_phase(PG8_LAS unsigned char* lds, const Gemm g, const Sched& S, const Epi& E) {
;     ...
;     for (int i = 0; i < 2; ++i) { int R, C; stage_rc(tid * 16 + i * 8192, R, C); const int Rb = Epi::PERM ? ((R & ~31) + perm32(R & 31)) : R;
;         voffA[i] = (unsigned)(R * K + C) * 2u; voffB[i] = (unsigned)(Rb * K + C) * 2u; }
;     const size_t kstep = (size_t)(BK * 2);
;     const size_t hstep = (size_t)HALF * K * 2;
;     const size_t tstep = 2 * hstep;
;     const unsigned ldsw = (unsigned)wid * 1024u;
;     const int aoff = lds_byte(wr * 64 + fr, fq * 8), boff = lds_byte(wc * 32 + fr, fq * 8);
;     ...
;     if constexpr (SP2) {
;         PG8_STAGE(PG8_SB(0, 0), cB, voffB); PG8_STAGE(PG8_SB(0, 1), cB + hstep, voffB); PG8_STAGE(PG8_SA(0, 0), cA, voffA); PG8_STAGE(PG8_SA(0, 1), cA + hstep, voffA);
;         if (wr == 1) PG8_BAR;
;         PG8_WAIT_V(2); PG8_BAR;
;         PG8_STAGE(PG8_SB(1, 0), cB + kstep, voffB); PG8_STAGE(PG8_SA(1, 0), cA + kstep, voffA); PG8_STAGE(PG8_SB(1, 1), cB + hstep + kstep, voffB);
;         PG8_WAIT_V(6); PG8_BAR;
.LBB0_220:
	v_mov_b32_e32 v133, v3
	v_bfe_u32 v13, v2, 4, 2
	v_lshl_add_u64 v[4:5], s[30:31], 0, v[132:133]
	v_mov_b32_e32 v1, v3
	v_and_b32_e32 v12, 15, v2
	v_lshlrev_b32_e32 v14, 4, v13
	v_lshlrev_b32_e32 v2, 2, v2
	s_lshl_b32 s7, s7, 5
	v_lshl_add_u64 v[6:7], s[30:31], 0, v[0:1]
	v_lshl_or_b32 v154, s16, 6, v12
	v_lshl_or_b32 v12, v12, 6, v14
	s_lshl_b32 s16, s16, 13
	v_and_b32_e32 v2, 32, v2
	s_and_b32 s7, s7, 0x60
	s_add_i32 m0, s42, 0x18000
	v_lshl_add_u64 v[4:5], v[4:5], 0, s[92:93]
	v_lshl_add_u64 v[8:9], s[28:29], 0, v[132:133]
	v_bitop3_b32 v14, v12, s16, v2 bitop3:0xde
	s_lshl_b32 s16, s7, 7
	global_load_lds_dwordx4 v[4:5], off
	v_lshl_add_u64 v[4:5], v[6:7], 0, s[92:93]
	s_add_i32 m0, s42, 0x1a000
	s_add_i32 s46, s42, 0x8000
	s_add_i32 s47, s42, 0xa000
	v_lshl_add_u64 v[10:11], s[28:29], 0, v[0:1]
	v_bitop3_b32 v155, v12, s16, v2 bitop3:0xde
	global_load_lds_dwordx4 v[4:5], off
	v_lshl_add_u64 v[4:5], v[8:9], 0, s[92:93]
	s_mov_b32 m0, s46
	s_add_u32 s16, s30, 0x10080
	global_load_lds_dwordx4 v[4:5], off
	v_lshl_add_u64 v[4:5], v[10:11], 0, s[92:93]
	s_mov_b32 m0, s47
	s_addc_u32 s17, s31, 0
	global_load_lds_dwordx4 v[4:5], off
	s_add_i32 m0, s42, 0x1c000
	v_lshl_add_u64 v[4:5], s[16:17], 0, v[132:133]
	global_load_lds_dwordx4 v[4:5], off
	v_lshl_add_u64 v[4:5], s[16:17], 0, v[0:1]
	s_add_i32 m0, s42, 0x1e000
	s_cmpk_lt_u32 s6, 0x100
	global_load_lds_dwordx4 v[4:5], off
	s_waitcnt vmcnt(8)
	s_barrier
	s_waitcnt vmcnt(6)
	s_cselect_b64 s[16:17], -1, 0
	v_lshlrev_b32_e32 v2, 2, v13
	s_lshl_b32 s84, s7, 1
	v_readlane_b32 s18, v254, 59
	v_readlane_b32 s6, v254, 39
	v_add_u32_e32 v156, 0, v14
	v_lshlrev_b32_e32 v2, 1, v2
	v_readlane_b32 s19, v254, 60
	v_readlane_b32 s48, v254, 38
	s_mov_b32 s49, s6
	s_barrier
	v_readlane_b32 s7, v254, 40
	s_branch .LBB0_223

; #define PG8_STAGE(bufoff, gbase, voff) do { _Pragma("unroll") for (int _i = 0; _i < 2; ++_i) \
;         __builtin_amdgcn_global_load_lds((const unsigned*)((const char*)(gbase) + (voff)[_i]), (PG8_LAS unsigned*)(lds + (bufoff) + ldsw + _i * 8192), 16, 0, 0); } while (0)
; #define PG8_WAIT_V(n) asm volatile("s_waitcnt vmcnt(" #n ")" ::: "memory")
; #define PG8_BAR __builtin_amdgcn_s_barrier()
; template <class Epi, class Sched, bool ALIGN_EPI = false, bool SP2 = false, bool NAT = false>
; __device__ __forceinline__ void gemm_phase(PG8_LAS unsigned char* lds, const Gemm g, const Sched& S, const Epi& E) {
;     ...
;     for (int i = 0; i < 2; ++i) { int R, C; stage_rc(tid * 16 + i * 8192, R, C); const int Rb = Epi::PERM ? ((R & ~31) + perm32(R & 31)) : R;
;         voffA[i] = (unsigned)(R * K + C) * 2u; voffB[i] = (unsigned)(Rb * K + C) * 2u; }
;     const size_t kstep = (size_t)(BK * 2);
;     const size_t hstep = (size_t)HALF * K * 2;
;     const size_t tstep = 2 * hstep;
;     const unsigned ldsw = (unsigned)wid * 1024u;
;     const int aoff = lds_byte(wr * 64 + fr, fq * 8), boff = lds_byte(wc * 32 + fr, fq * 8);
;     ...
;     if constexpr (SP2) {
;         PG8_STAGE(PG8_SB(0, 0), cB, voffB); PG8_STAGE(PG8_SB(0, 1), cB + hstep, voffB); PG8_STAGE(PG8_SA(0, 0), cA, voffA); PG8_STAGE(PG8_SA(0, 1), cA + hstep, voffA);
;         if (wr == 1) PG8_BAR;
;         PG8_WAIT_V(2); PG8_BAR;
;         PG8_STAGE(PG8_SB(1, 0), cB + kstep, voffB); PG8_STAGE(PG8_SA(1, 0), cA + kstep, voffA); PG8_STAGE(PG8_SB(1, 1), cB + hstep + kstep, voffB);
;         PG8_WAIT_V(6); PG8_BAR;
.LBB0_238:
	v_mov_b32_e32 v133, v3
	v_lshl_add_u64 v[4:5], s[24:25], 0, v[132:133]
	v_mov_b32_e32 v1, v3
	v_bfe_u32 v13, v2, 4, 2
	s_lshl_b32 s14, s7, 5
	v_lshl_add_u64 v[6:7], s[24:25], 0, v[0:1]
	v_and_b32_e32 v12, 15, v2
	v_lshlrev_b32_e32 v14, 4, v13
	v_lshlrev_b32_e32 v2, 2, v2
	s_and_b32 s37, s14, 0x60
	s_add_i32 m0, s31, 0x18000
	v_lshl_add_u64 v[4:5], v[4:5], 0, s[92:93]
	v_lshl_add_u64 v[8:9], s[22:23], 0, v[132:133]
	s_lshl_b32 s36, s12, 6
	v_lshl_or_b32 v14, v12, 6, v14
	s_lshl_b32 s12, s12, 13
	v_and_b32_e32 v2, 32, v2
	s_lshl_b32 s7, s37, 7
	global_load_lds_dwordx4 v[4:5], off
	v_lshl_add_u64 v[4:5], v[6:7], 0, s[92:93]
	s_add_i32 m0, s31, 0x1a000
	s_add_i32 s38, s31, 0x8000
	s_add_i32 s39, s31, 0xa000
	v_lshl_add_u64 v[10:11], s[22:23], 0, v[0:1]
	v_bitop3_b32 v15, v14, s12, v2 bitop3:0xde
	global_load_lds_dwordx4 v[4:5], off
	v_lshl_add_u64 v[4:5], v[8:9], 0, s[92:93]
	s_mov_b32 m0, s38
	s_add_u32 s12, s24, 0x10080
	global_load_lds_dwordx4 v[4:5], off
	v_lshl_add_u64 v[4:5], v[10:11], 0, s[92:93]
	s_mov_b32 m0, s39
	s_addc_u32 s13, s25, 0
	global_load_lds_dwordx4 v[4:5], off
	s_add_i32 m0, s31, 0x1c000
	v_lshl_add_u64 v[4:5], s[12:13], 0, v[132:133]
	global_load_lds_dwordx4 v[4:5], off
	v_lshl_add_u64 v[4:5], s[12:13], 0, v[0:1]
	s_add_i32 m0, s31, 0x1e000
	v_bitop3_b32 v135, v14, s7, v2 bitop3:0xde
	global_load_lds_dwordx4 v[4:5], off
	v_and_or_b32 v2, s14, 32, v12
	s_waitcnt vmcnt(8)
	s_barrier
	s_waitcnt vmcnt(6)
	v_lshlrev_b32_e32 v2, 7, v2
	s_cmpk_lt_u32 s6, 0x100
	s_waitcnt lgkmcnt(0)
	v_lshl_add_u64 v[136:137], s[4:5], 0, v[2:3]
	v_readlane_b32 s12, v254, 59
	v_readlane_b32 s4, v254, 39
	s_cselect_b64 s[6:7], -1, 0
	v_lshlrev_b32_e32 v134, 2, v13
	v_add_u32_e32 v156, 0, v15
	v_readlane_b32 s13, v254, 60
	v_readlane_b32 s42, v254, 38
	s_mov_b32 s43, s4
	s_barrier
	v_readlane_b32 s5, v254, 40
	s_branch .LBB0_241

; #define PG8_STAGE(bufoff, gbase, voff) do { _Pragma("unroll") for (int _i = 0; _i < 2; ++_i) \
;         __builtin_amdgcn_global_load_lds((const unsigned*)((const char*)(gbase) + (voff)[_i]), (PG8_LAS unsigned*)(lds + (bufoff) + ldsw + _i * 8192), 16, 0, 0); } while (0)
; #define PG8_WAIT_V(n) asm volatile("s_waitcnt vmcnt(" #n ")" ::: "memory")
; #define PG8_BAR __builtin_amdgcn_s_barrier()
; template <class Epi, class Sched, bool ALIGN_EPI = false, bool SP2 = false, bool NAT = false>
; __device__ __forceinline__ void gemm_phase(PG8_LAS unsigned char* lds, const Gemm g, const Sched& S, const Epi& E) {
;     ...
;     for (int i = 0; i < 2; ++i) { int R, C; stage_rc(tid * 16 + i * 8192, R, C); const int Rb = Epi::PERM ? ((R & ~31) + perm32(R & 31)) : R;
;         voffA[i] = (unsigned)(R * K + C) * 2u; voffB[i] = (unsigned)(Rb * K + C) * 2u; }
;     const size_t kstep = (size_t)(BK * 2);
;     const size_t hstep = (size_t)HALF * K * 2;
;     const size_t tstep = 2 * hstep;
;     const unsigned ldsw = (unsigned)wid * 1024u;
;     const int aoff = lds_byte(wr * 64 + fr, fq * 8), boff = lds_byte(wc * 32 + fr, fq * 8);
;     ...
;     if constexpr (SP2) {
;         PG8_STAGE(PG8_SB(0, 0), cB, voffB); PG8_STAGE(PG8_SB(0, 1), cB + hstep, voffB); PG8_STAGE(PG8_SA(0, 0), cA, voffA); PG8_STAGE(PG8_SA(0, 1), cA + hstep, voffA);
;         if (wr == 1) PG8_BAR;
;         PG8_WAIT_V(2); PG8_BAR;
;         PG8_STAGE(PG8_SB(1, 0), cB + kstep, voffB); PG8_STAGE(PG8_SA(1, 0), cA + kstep, voffA); PG8_STAGE(PG8_SB(1, 1), cB + hstep + kstep, voffB);
;         PG8_WAIT_V(6); PG8_BAR;
.LBB0_361:
	s_lshl_b32 s6, s6, 5
	s_and_b32 s38, s6, 0x60
	s_add_i32 m0, s34, 0x18000
	v_lshl_add_u64 v[10:11], v[10:11], 0, s[92:93]
	s_lshl_b32 s20, s5, 13
	s_lshl_b32 s21, s38, 7
	global_load_lds_dwordx4 v[10:11], off
	v_lshl_add_u64 v[8:9], v[8:9], 0, s[92:93]
	s_add_i32 m0, s34, 0x1a000
	s_add_i32 s39, s34, 0x8000
	s_add_i32 s44, s34, 0xa000
	global_load_lds_dwordx4 v[8:9], off
	v_lshl_add_u64 v[4:5], v[4:5], 0, s[92:93]
	s_mov_b32 m0, s39
	s_add_u32 s6, s28, 0x18080
	global_load_lds_dwordx4 v[4:5], off
	v_lshl_add_u64 v[4:5], v[6:7], 0, s[92:93]
	s_mov_b32 m0, s44
	s_addc_u32 s7, s29, 0
	global_load_lds_dwordx4 v[4:5], off
	s_add_i32 m0, s34, 0x1c000
	v_lshl_add_u64 v[4:5], s[6:7], 0, v[132:133]
	global_load_lds_dwordx4 v[4:5], off
	v_lshl_add_u64 v[4:5], s[6:7], 0, v[0:1]
	s_add_i32 m0, s34, 0x1e000
	s_cmpk_lt_u32 s4, 0x100
	global_load_lds_dwordx4 v[4:5], off
	v_bfe_u32 v5, v2, 4, 2
	v_and_b32_e32 v4, 15, v2
	v_lshlrev_b32_e32 v6, 4, v5
	v_lshlrev_b32_e32 v2, 2, v2
	v_lshl_or_b32 v137, s5, 6, v4
	v_lshl_or_b32 v4, v4, 6, v6
	v_and_b32_e32 v2, 32, v2
	v_bitop3_b32 v6, v4, s20, v2 bitop3:0xde
	v_bitop3_b32 v161, v4, s21, v2 bitop3:0xde
	s_cselect_b64 s[20:21], -1, 0
	s_lshl_b32 s4, s38, 1
	s_waitcnt vmcnt(8)
	s_barrier
	s_waitcnt vmcnt(6)
	s_waitcnt lgkmcnt(0)
	s_add_u32 s4, s10, s4
	v_lshlrev_b32_e32 v134, 3, v5
	s_addc_u32 s5, s11, 0
	v_mov_b32_e32 v135, v3
	v_readlane_b32 s10, v254, 59
	v_add_u32_e32 v162, 0, v6
	v_lshlrev_b32_e32 v136, 2, v5
	v_lshl_add_u64 v[154:155], s[4:5], 0, v[134:135]
	v_readlane_b32 s11, v254, 60
	v_readlane_b32 s33, v254, 36
	v_readlane_b32 s47, v254, 33
	s_barrier
	s_branch .LBB0_364

; #define PG8_STAGE(bufoff, gbase, voff) do { _Pragma("unroll") for (int _i = 0; _i < 2; ++_i) \
;         __builtin_amdgcn_global_load_lds((const unsigned*)((const char*)(gbase) + (voff)[_i]), (PG8_LAS unsigned*)(lds + (bufoff) + ldsw + _i * 8192), 16, 0, 0); } while (0)
; #define PG8_WAIT_V(n) asm volatile("s_waitcnt vmcnt(" #n ")" ::: "memory")
; #define PG8_BAR __builtin_amdgcn_s_barrier()
; template <class Epi, class Sched, bool ALIGN_EPI = false, bool SP2 = false, bool NAT = false>
; __device__ __forceinline__ void gemm_phase(PG8_LAS unsigned char* lds, const Gemm g, const Sched& S, const Epi& E) {
;     ...
;     for (int i = 0; i < 2; ++i) { int R, C; stage_rc(tid * 16 + i * 8192, R, C); const int Rb = Epi::PERM ? ((R & ~31) + perm32(R & 31)) : R;
;         voffA[i] = (unsigned)(R * K + C) * 2u; voffB[i] = (unsigned)(Rb * K + C) * 2u; }
;     const size_t kstep = (size_t)(BK * 2);
;     const size_t hstep = (size_t)HALF * K * 2;
;     const size_t tstep = 2 * hstep;
;     const unsigned ldsw = (unsigned)wid * 1024u;
;     const int aoff = lds_byte(wr * 64 + fr, fq * 8), boff = lds_byte(wc * 32 + fr, fq * 8);
;     ...
;     if constexpr (SP2) {
;         PG8_STAGE(PG8_SB(0, 0), cB, voffB); PG8_STAGE(PG8_SB(0, 1), cB + hstep, voffB); PG8_STAGE(PG8_SA(0, 0), cA, voffA); PG8_STAGE(PG8_SA(0, 1), cA + hstep, voffA);
;         if (wr == 1) PG8_BAR;
;         PG8_WAIT_V(2); PG8_BAR;
;         PG8_STAGE(PG8_SB(1, 0), cB + kstep, voffB); PG8_STAGE(PG8_SA(1, 0), cA + kstep, voffA); PG8_STAGE(PG8_SB(1, 1), cB + hstep + kstep, voffB);
;         PG8_WAIT_V(6); PG8_BAR;
.LBB0_411:
	v_mov_b32_e32 v133, v3
	v_bfe_u32 v13, v2, 4, 2
	v_lshl_add_u64 v[4:5], s[34:35], 0, v[132:133]
	v_mov_b32_e32 v1, v3
	v_and_b32_e32 v12, 15, v2
	v_lshlrev_b32_e32 v14, 4, v13
	v_lshlrev_b32_e32 v2, 2, v2
	s_lshl_b32 s7, s7, 5
	v_lshl_add_u64 v[6:7], s[34:35], 0, v[0:1]
	v_lshl_or_b32 v154, s18, 6, v12
	v_lshl_or_b32 v12, v12, 6, v14
	s_lshl_b32 s18, s18, 13
	v_and_b32_e32 v2, 32, v2
	s_and_b32 s7, s7, 0x60
	s_add_i32 m0, s45, 0x18000
	v_lshl_add_u64 v[4:5], v[4:5], 0, s[92:93]
	v_lshl_add_u64 v[8:9], s[30:31], 0, v[132:133]
	v_bitop3_b32 v14, v12, s18, v2 bitop3:0xde
	s_lshl_b32 s18, s7, 7
	global_load_lds_dwordx4 v[4:5], off
	v_lshl_add_u64 v[4:5], v[6:7], 0, s[92:93]
	s_add_i32 m0, s45, 0x1a000
	s_add_i32 s49, s45, 0x8000
	s_add_i32 s50, s45, 0xa000
	v_lshl_add_u64 v[10:11], s[30:31], 0, v[0:1]
	v_bitop3_b32 v155, v12, s18, v2 bitop3:0xde
	global_load_lds_dwordx4 v[4:5], off
	v_lshl_add_u64 v[4:5], v[8:9], 0, s[92:93]
	s_mov_b32 m0, s49
	s_add_u32 s18, s34, 0x10080
	global_load_lds_dwordx4 v[4:5], off
	v_lshl_add_u64 v[4:5], v[10:11], 0, s[92:93]
	s_mov_b32 m0, s50
	s_addc_u32 s19, s35, 0
	global_load_lds_dwordx4 v[4:5], off
	s_add_i32 m0, s45, 0x1c000
	v_lshl_add_u64 v[4:5], s[18:19], 0, v[132:133]
	global_load_lds_dwordx4 v[4:5], off
	v_lshl_add_u64 v[4:5], s[18:19], 0, v[0:1]
	s_add_i32 m0, s45, 0x1e000
	s_cmpk_lt_u32 s6, 0x100
	global_load_lds_dwordx4 v[4:5], off
	s_waitcnt vmcnt(8)
	s_barrier
	s_waitcnt vmcnt(6)
	s_cselect_b64 s[18:19], -1, 0
	v_lshlrev_b32_e32 v2, 2, v13
	s_lshl_b32 s84, s7, 1
	v_readlane_b32 s20, v254, 59
	v_readlane_b32 s6, v254, 39
	v_add_u32_e32 v156, 0, v14
	v_lshlrev_b32_e32 v2, 1, v2
	v_readlane_b32 s21, v254, 60
	v_readlane_b32 s51, v254, 38
	s_mov_b32 s52, s6
	s_barrier
	v_readlane_b32 s7, v254, 40
	s_branch .LBB0_414

; #define PG8_STAGE(bufoff, gbase, voff) do { _Pragma("unroll") for (int _i = 0; _i < 2; ++_i) \
;         __builtin_amdgcn_global_load_lds((const unsigned*)((const char*)(gbase) + (voff)[_i]), (PG8_LAS unsigned*)(lds + (bufoff) + ldsw + _i * 8192), 16, 0, 0); } while (0)
; #define PG8_WAIT_V(n) asm volatile("s_waitcnt vmcnt(" #n ")" ::: "memory")
; #define PG8_BAR __builtin_amdgcn_s_barrier()
; template <class Epi, class Sched, bool ALIGN_EPI = false, bool SP2 = false, bool NAT = false>
; __device__ __forceinline__ void gemm_phase(PG8_LAS unsigned char* lds, const Gemm g, const Sched& S, const Epi& E) {
;     ...
;     for (int i = 0; i < 2; ++i) { int R, C; stage_rc(tid * 16 + i * 8192, R, C); const int Rb = Epi::PERM ? ((R & ~31) + perm32(R & 31)) : R;
;         voffA[i] = (unsigned)(R * K + C) * 2u; voffB[i] = (unsigned)(Rb * K + C) * 2u; }
;     const size_t kstep = (size_t)(BK * 2);
;     const size_t hstep = (size_t)HALF * K * 2;
;     const size_t tstep = 2 * hstep;
;     const unsigned ldsw = (unsigned)wid * 1024u;
;     const int aoff = lds_byte(wr * 64 + fr, fq * 8), boff = lds_byte(wc * 32 + fr, fq * 8);
;     ...
;     if constexpr (SP2) {
;         PG8_STAGE(PG8_SB(0, 0), cB, voffB); PG8_STAGE(PG8_SB(0, 1), cB + hstep, voffB); PG8_STAGE(PG8_SA(0, 0), cA, voffA); PG8_STAGE(PG8_SA(0, 1), cA + hstep, voffA);
;         if (wr == 1) PG8_BAR;
;         PG8_WAIT_V(2); PG8_BAR;
;         PG8_STAGE(PG8_SB(1, 0), cB + kstep, voffB); PG8_STAGE(PG8_SA(1, 0), cA + kstep, voffA); PG8_STAGE(PG8_SB(1, 1), cB + hstep + kstep, voffB);
;         PG8_WAIT_V(6); PG8_BAR;
.LBB0_429:
	v_mov_b32_e32 v133, v3
	v_bfe_u32 v13, v2, 4, 2
	v_lshl_add_u64 v[4:5], s[28:29], 0, v[132:133]
	v_mov_b32_e32 v1, v3
	v_and_b32_e32 v12, 15, v2
	v_lshlrev_b32_e32 v14, 4, v13
	v_lshlrev_b32_e32 v2, 2, v2
	s_lshl_b32 s5, s5, 5
	v_lshl_add_u64 v[6:7], s[28:29], 0, v[0:1]
	s_lshl_b32 s43, s14, 6
	v_lshl_or_b32 v14, v12, 6, v14
	s_lshl_b32 s14, s14, 13
	v_and_b32_e32 v2, 32, v2
	s_and_b32 s44, s5, 0x60
	s_add_i32 m0, s37, 0x18000
	v_lshl_add_u64 v[4:5], v[4:5], 0, s[92:93]
	v_lshl_add_u64 v[8:9], s[26:27], 0, v[132:133]
	v_bitop3_b32 v15, v14, s14, v2 bitop3:0xde
	s_lshl_b32 s14, s44, 7
	global_load_lds_dwordx4 v[4:5], off
	v_lshl_add_u64 v[4:5], v[6:7], 0, s[92:93]
	s_add_i32 m0, s37, 0x1a000
	s_add_i32 s45, s37, 0x8000
	s_add_i32 s46, s37, 0xa000
	v_lshl_add_u64 v[10:11], s[26:27], 0, v[0:1]
	v_bitop3_b32 v135, v14, s14, v2 bitop3:0xde
	global_load_lds_dwordx4 v[4:5], off
	v_lshl_add_u64 v[4:5], v[8:9], 0, s[92:93]
	s_mov_b32 m0, s45
	s_add_u32 s14, s28, 0x10080
	global_load_lds_dwordx4 v[4:5], off
	v_lshl_add_u64 v[4:5], v[10:11], 0, s[92:93]
	s_mov_b32 m0, s46
	s_addc_u32 s15, s29, 0
	global_load_lds_dwordx4 v[4:5], off
	s_add_i32 m0, s37, 0x1c000
	v_lshl_add_u64 v[4:5], s[14:15], 0, v[132:133]
	global_load_lds_dwordx4 v[4:5], off
	v_lshl_add_u64 v[4:5], s[14:15], 0, v[0:1]
	s_add_i32 m0, s37, 0x1e000
	s_cmpk_lt_u32 s4, 0x100
	global_load_lds_dwordx4 v[4:5], off
	s_waitcnt vmcnt(8)
	s_barrier
	s_waitcnt vmcnt(6)
	s_barrier
	v_and_or_b32 v2, s5, 32, v12
	s_load_dwordx2 s[4:5], s[0:1], 0x140
	v_lshlrev_b32_e32 v2, 7, v2
	v_readlane_b32 s16, v254, 59
	s_cselect_b64 s[14:15], -1, 0
	v_lshlrev_b32_e32 v134, 2, v13
	s_waitcnt lgkmcnt(0)
	v_lshl_add_u64 v[136:137], s[4:5], 0, v[2:3]
	v_readlane_b32 s4, v254, 39
	v_add_u32_e32 v156, 0, v15
	v_readlane_b32 s17, v254, 60
	v_readlane_b32 s47, v254, 38
	s_mov_b32 s48, s4
	v_readlane_b32 s5, v254, 40
	s_branch .LBB0_432

; #define PG8_STAGE(bufoff, gbase, voff) do { _Pragma("unroll") for (int _i = 0; _i < 2; ++_i) \
;         __builtin_amdgcn_global_load_lds((const unsigned*)((const char*)(gbase) + (voff)[_i]), (PG8_LAS unsigned*)(lds + (bufoff) + ldsw + _i * 8192), 16, 0, 0); } while (0)
; #define PG8_WAIT_V(n) asm volatile("s_waitcnt vmcnt(" #n ")" ::: "memory")
; #define PG8_BAR __builtin_amdgcn_s_barrier()
; template <class Epi, class Sched, bool ALIGN_EPI = false, bool SP2 = false, bool NAT = false>
; __device__ __forceinline__ void gemm_phase(PG8_LAS unsigned char* lds, const Gemm g, const Sched& S, const Epi& E) {
;     ...
;     for (int i = 0; i < 2; ++i) { int R, C; stage_rc(tid * 16 + i * 8192, R, C); const int Rb = Epi::PERM ? ((R & ~31) + perm32(R & 31)) : R;
;         voffA[i] = (unsigned)(R * K + C) * 2u; voffB[i] = (unsigned)(Rb * K + C) * 2u; }
;     const size_t kstep = (size_t)(BK * 2);
;     const size_t hstep = (size_t)HALF * K * 2;
;     const size_t tstep = 2 * hstep;
;     const unsigned ldsw = (unsigned)wid * 1024u;
;     const int aoff = lds_byte(wr * 64 + fr, fq * 8), boff = lds_byte(wc * 32 + fr, fq * 8);
;     ...
;     if constexpr (SP2) {
;         PG8_STAGE(PG8_SB(0, 0), cB, voffB); PG8_STAGE(PG8_SB(0, 1), cB + hstep, voffB); PG8_STAGE(PG8_SA(0, 0), cA, voffA); PG8_STAGE(PG8_SA(0, 1), cA + hstep, voffA);
;         if (wr == 1) PG8_BAR;
;         PG8_WAIT_V(2); PG8_BAR;
;         PG8_STAGE(PG8_SB(1, 0), cB + kstep, voffB); PG8_STAGE(PG8_SA(1, 0), cA + kstep, voffA); PG8_STAGE(PG8_SB(1, 1), cB + hstep + kstep, voffB);
;         PG8_WAIT_V(6); PG8_BAR;
.LBB0_450:
	s_lshl_b32 s18, s18, 5
	s_and_b32 s21, s18, 0x60
	s_add_i32 m0, s37, 0x18000
	v_lshl_add_u64 v[10:11], v[10:11], 0, s[92:93]
	s_lshl_b32 s20, s5, 13
	s_lshl_b32 s22, s21, 7
	global_load_lds_dwordx4 v[10:11], off
	v_lshl_add_u64 v[8:9], v[8:9], 0, s[92:93]
	s_add_i32 m0, s37, 0x1a000
	s_add_i32 s43, s37, 0x8000
	s_add_i32 s44, s37, 0xa000
	global_load_lds_dwordx4 v[8:9], off
	v_lshl_add_u64 v[4:5], v[4:5], 0, s[92:93]
	s_mov_b32 m0, s43
	s_add_u32 s18, s28, 0x40080
	global_load_lds_dwordx4 v[4:5], off
	v_lshl_add_u64 v[4:5], v[6:7], 0, s[92:93]
	s_mov_b32 m0, s44
	s_addc_u32 s19, s29, 0
	global_load_lds_dwordx4 v[4:5], off
	s_add_i32 m0, s37, 0x1c000
	v_lshl_add_u64 v[4:5], s[18:19], 0, v[132:133]
	global_load_lds_dwordx4 v[4:5], off
	v_lshl_add_u64 v[4:5], s[18:19], 0, v[0:1]
	s_add_i32 m0, s37, 0x1e000
	s_cmpk_lt_u32 s4, 0x100
	global_load_lds_dwordx4 v[4:5], off
	v_bfe_u32 v5, v2, 4, 2
	v_and_b32_e32 v4, 15, v2
	v_lshlrev_b32_e32 v6, 4, v5
	v_lshlrev_b32_e32 v2, 2, v2
	v_lshl_or_b32 v158, s5, 6, v4
	v_lshl_or_b32 v4, v4, 6, v6
	v_and_b32_e32 v2, 32, v2
	v_bitop3_b32 v6, v4, s20, v2 bitop3:0xde
	v_bitop3_b32 v159, v4, s22, v2 bitop3:0xde
	v_lshlrev_b32_e32 v4, 14, v12
	v_and_b32_e32 v4, 0xffff8000, v4
	v_lshlrev_b32_e32 v2, 2, v5
	v_lshl_add_u32 v4, v13, 11, v4
	v_and_b32_e32 v5, 1, v12
	v_lshl_or_b32 v4, v5, 6, v4
	v_lshl_add_u32 v134, v14, 1, v4
	v_lshlrev_b32_e32 v4, 14, v15
	v_and_b32_e32 v4, 0xffff8000, v4
	s_waitcnt vmcnt(8)
	s_barrier
	s_waitcnt vmcnt(6)
	v_lshl_add_u32 v4, v16, 11, v4
	v_and_b32_e32 v5, 1, v15
	v_lshl_or_b32 v4, v5, 6, v4
	v_readlane_b32 s4, v254, 7
	s_cselect_b64 s[18:19], -1, 0
	v_mov_b32_e32 v135, v3
	v_lshl_add_u32 v136, v17, 1, v4
	v_mov_b32_e32 v137, v3
	s_mov_b32 s45, 0
	v_add_u32_e32 v160, 0, v6
	s_lshl_b32 s46, s21, 1
	v_lshlrev_b32_e32 v2, 1, v2
	v_readlane_b32 s48, v254, 6
	s_mov_b32 s47, s4
	s_barrier
	v_readlane_b32 s5, v254, 8
	s_branch .LBB0_453

; #define PG8_STAGE(bufoff, gbase, voff) do { _Pragma("unroll") for (int _i = 0; _i < 2; ++_i) \
;         __builtin_amdgcn_global_load_lds((const unsigned*)((const char*)(gbase) + (voff)[_i]), (PG8_LAS unsigned*)(lds + (bufoff) + ldsw + _i * 8192), 16, 0, 0); } while (0)
; #define PG8_WAIT_V(n) asm volatile("s_waitcnt vmcnt(" #n ")" ::: "memory")
; #define PG8_BAR __builtin_amdgcn_s_barrier()
; template <class Epi, class Sched, bool ALIGN_EPI = false, bool SP2 = false, bool NAT = false>
; __device__ __forceinline__ void gemm_phase(PG8_LAS unsigned char* lds, const Gemm g, const Sched& S, const Epi& E) {
;     ...
;     for (int i = 0; i < 2; ++i) { int R, C; stage_rc(tid * 16 + i * 8192, R, C); const int Rb = Epi::PERM ? ((R & ~31) + perm32(R & 31)) : R;
;         voffA[i] = (unsigned)(R * K + C) * 2u; voffB[i] = (unsigned)(Rb * K + C) * 2u; }
;     const size_t kstep = (size_t)(BK * 2);
;     const size_t hstep = (size_t)HALF * K * 2;
;     const size_t tstep = 2 * hstep;
;     const unsigned ldsw = (unsigned)wid * 1024u;
;     const int aoff = lds_byte(wr * 64 + fr, fq * 8), boff = lds_byte(wc * 32 + fr, fq * 8);
;     ...
;     if constexpr (SP2) {
;         PG8_STAGE(PG8_SB(0, 0), cB, voffB); PG8_STAGE(PG8_SB(0, 1), cB + hstep, voffB); PG8_STAGE(PG8_SA(0, 0), cA, voffA); PG8_STAGE(PG8_SA(0, 1), cA + hstep, voffA);
;         if (wr == 1) PG8_BAR;
;         PG8_WAIT_V(2); PG8_BAR;
;         PG8_STAGE(PG8_SB(1, 0), cB + kstep, voffB); PG8_STAGE(PG8_SA(1, 0), cA + kstep, voffA); PG8_STAGE(PG8_SB(1, 1), cB + hstep + kstep, voffB);
;         PG8_WAIT_V(6); PG8_BAR;
.LBB0_473:
	v_readlane_b32 s15, v255, 8
	s_add_u32 s33, s4, s15
	s_addc_u32 s34, s5, 0
	s_lshl_b32 s4, s7, 5
	s_and_b32 s7, s4, 0x60
	s_add_i32 m0, s28, 0x18000
	v_lshl_add_u64 v[10:11], v[10:11], 0, s[92:93]
	s_lshl_b32 s35, s14, 6
	s_lshl_b32 s14, s14, 13
	s_lshl_b32 s15, s7, 7
	global_load_lds_dwordx4 v[10:11], off
	v_lshl_add_u64 v[8:9], v[8:9], 0, s[92:93]
	s_add_i32 m0, s28, 0x1a000
	s_add_i32 s36, s28, 0x8000
	s_add_i32 s37, s28, 0xa000
	global_load_lds_dwordx4 v[8:9], off
	v_lshl_add_u64 v[4:5], v[4:5], 0, s[92:93]
	s_mov_b32 m0, s36
	s_add_u32 s4, s20, 0xb0080
	global_load_lds_dwordx4 v[4:5], off
	v_lshl_add_u64 v[4:5], v[6:7], 0, s[92:93]
	s_mov_b32 m0, s37
	s_addc_u32 s5, s21, 0
	global_load_lds_dwordx4 v[4:5], off
	s_add_i32 m0, s28, 0x1c000
	v_lshl_add_u64 v[4:5], s[4:5], 0, v[2:3]
	global_load_lds_dwordx4 v[4:5], off
	v_lshl_add_u64 v[4:5], s[4:5], 0, v[0:1]
	s_add_i32 m0, s28, 0x1e000
	v_and_b32_e32 v170, 15, v12
	global_load_lds_dwordx4 v[4:5], off
	v_bfe_u32 v4, v12, 4, 2
	v_lshlrev_b32_e32 v5, 4, v4
	v_lshlrev_b32_e32 v6, 2, v12
	v_lshl_or_b32 v5, v170, 6, v5
	v_and_b32_e32 v6, 32, v6
	s_cmpk_lt_u32 s6, 0x100
	s_movk_i32 s6, 0xb00
	v_bitop3_b32 v7, v5, s14, v6 bitop3:0xde
	v_bitop3_b32 v171, v5, s15, v6 bitop3:0xde
	v_lshl_or_b32 v172, v4, 2, s7
	v_lshrrev_b32_e32 v5, 1, v13
	v_mul_lo_u32 v4, v14, s6
	s_mov_b32 s7, 0xb000
	v_mad_u64_u32 v[4:5], s[4:5], v5, s7, v[4:5]
	v_or_b32_e32 v4, v4, v15
	v_add_lshl_u32 v4, v4, v16, 1
	v_mov_b32_e32 v5, v3
	s_mov_b64 s[16:17], 0xb0080
	v_lshl_add_u64 v[132:133], v[4:5], 0, s[16:17]
	v_lshrrev_b32_e32 v5, 1, v18
	v_mul_lo_u32 v4, v17, s6
	v_mad_u64_u32 v[4:5], s[4:5], v5, s7, v[4:5]
	s_waitcnt vmcnt(8)
	s_barrier
	s_waitcnt vmcnt(6)
	v_or_b32_e32 v4, v4, v19
	v_add_lshl_u32 v4, v4, v20, 1
	v_mov_b32_e32 v5, v3
	v_readlane_b32 s4, v254, 46
	s_cselect_b64 s[14:15], -1, 0
	v_lshl_add_u64 v[134:135], v[4:5], 0, s[16:17]
	s_mov_b32 s38, 0
	v_add_u32_e32 v173, 0, v7
	v_readlane_b32 s43, v254, 45
	s_mov_b32 s44, s4
	s_barrier
	v_readlane_b32 s5, v254, 47
	s_branch .LBB0_476

; #define PG8_STAGE(bufoff, gbase, voff) do { _Pragma("unroll") for (int _i = 0; _i < 2; ++_i) \
;         __builtin_amdgcn_global_load_lds((const unsigned*)((const char*)(gbase) + (voff)[_i]), (PG8_LAS unsigned*)(lds + (bufoff) + ldsw + _i * 8192), 16, 0, 0); } while (0)
; #define PG8_WAIT_V(n) asm volatile("s_waitcnt vmcnt(" #n ")" ::: "memory")
; #define PG8_BAR __builtin_amdgcn_s_barrier()
; template <class Epi, class Sched, bool ALIGN_EPI = false, bool SP2 = false, bool NAT = false>
; __device__ __forceinline__ void gemm_phase(PG8_LAS unsigned char* lds, const Gemm g, const Sched& S, const Epi& E) {
;     ...
;     for (int i = 0; i < 2; ++i) { int R, C; stage_rc(tid * 16 + i * 8192, R, C); const int Rb = Epi::PERM ? ((R & ~31) + perm32(R & 31)) : R;
;         voffA[i] = (unsigned)(R * K + C) * 2u; voffB[i] = (unsigned)(Rb * K + C) * 2u; }
;     const size_t kstep = (size_t)(BK * 2);
;     const size_t hstep = (size_t)HALF * K * 2;
;     const size_t tstep = 2 * hstep;
;     const unsigned ldsw = (unsigned)wid * 1024u;
;     const int aoff = lds_byte(wr * 64 + fr, fq * 8), boff = lds_byte(wc * 32 + fr, fq * 8);
;     ...
;     if constexpr (SP2) {
;         PG8_STAGE(PG8_SB(0, 0), cB, voffB); PG8_STAGE(PG8_SB(0, 1), cB + hstep, voffB); PG8_STAGE(PG8_SA(0, 0), cA, voffA); PG8_STAGE(PG8_SA(0, 1), cA + hstep, voffA);
;         if (wr == 1) PG8_BAR;
;         PG8_WAIT_V(2); PG8_BAR;
;         PG8_STAGE(PG8_SB(1, 0), cB + kstep, voffB); PG8_STAGE(PG8_SA(1, 0), cA + kstep, voffA); PG8_STAGE(PG8_SB(1, 1), cB + hstep + kstep, voffB);
;         PG8_WAIT_V(6); PG8_BAR;
.LBB0_502:
	v_mov_b32_e32 v133, v3
	v_lshl_add_u64 v[10:11], s[20:21], 0, v[132:133]
	v_mov_b32_e32 v1, v3
	v_lshl_add_u64 v[12:13], s[20:21], 0, v[0:1]
	s_and_b32 s5, s5, 3
	s_add_i32 m0, s28, 0x18000
	v_lshl_add_u64 v[10:11], v[10:11], 0, s[92:93]
	v_lshl_add_u64 v[14:15], s[22:23], 0, v[132:133]
	s_lshl_b32 s11, s4, 13
	s_lshl_b32 s14, s5, 12
	global_load_lds_dwordx4 v[10:11], off
	v_lshl_add_u64 v[10:11], v[12:13], 0, s[92:93]
	s_add_i32 m0, s28, 0x1a000
	s_add_i32 s34, s28, 0x8000
	s_add_i32 s35, s28, 0xa000
	v_lshl_add_u64 v[16:17], s[22:23], 0, v[0:1]
	global_load_lds_dwordx4 v[10:11], off
	v_lshl_add_u64 v[10:11], v[14:15], 0, s[92:93]
	s_mov_b32 m0, s34
	s_add_u32 s12, s20, 0x40080
	global_load_lds_dwordx4 v[10:11], off
	v_lshl_add_u64 v[10:11], v[16:17], 0, s[92:93]
	s_mov_b32 m0, s35
	s_addc_u32 s13, s21, 0
	global_load_lds_dwordx4 v[10:11], off
	s_add_i32 m0, s28, 0x1c000
	v_lshl_add_u64 v[10:11], s[12:13], 0, v[132:133]
	global_load_lds_dwordx4 v[10:11], off
	v_lshl_add_u64 v[10:11], s[12:13], 0, v[0:1]
	s_add_i32 m0, s28, 0x1e000
	s_cmpk_lt_u32 s10, 0x100
	global_load_lds_dwordx4 v[10:11], off
	v_bfe_u32 v11, v2, 4, 2
	v_and_b32_e32 v10, 15, v2
	v_lshlrev_b32_e32 v12, 4, v11
	v_lshlrev_b32_e32 v2, 2, v2
	v_lshl_or_b32 v156, s4, 6, v10
	v_lshl_or_b32 v10, v10, 6, v12
	v_and_b32_e32 v2, 32, v2
	v_bitop3_b32 v12, v10, s11, v2 bitop3:0xde
	v_bitop3_b32 v157, v10, s14, v2 bitop3:0xde
	v_lshlrev_b32_e32 v10, 14, v4
	v_and_b32_e32 v10, 0xffff8000, v10
	v_lshl_add_u32 v5, v5, 11, v10
	v_and_b32_e32 v4, 1, v4
	v_lshl_or_b32 v4, v4, 6, v5
	v_lshl_add_u32 v134, v6, 1, v4
	v_lshlrev_b32_e32 v4, 14, v7
	v_and_b32_e32 v4, 0xffff8000, v4
	s_waitcnt vmcnt(8)
	s_barrier
	s_waitcnt vmcnt(6)
	s_cselect_b64 s[10:11], -1, 0
	s_lshl_b32 s4, s5, 4
	v_lshl_add_u32 v4, v8, 11, v4
	v_and_b32_e32 v5, 1, v7
	v_lshlrev_b32_e32 v2, 2, v11
	v_lshl_or_b32 v4, v5, 6, v4
	s_lshl_b32 s84, s4, 1
	v_readlane_b32 s4, v254, 23
	v_mov_b32_e32 v135, v3
	v_lshl_add_u32 v136, v9, 1, v4
	v_mov_b32_e32 v137, v3
	s_mov_b32 s36, 0
	v_add_u32_e32 v158, 0, v12
	v_lshlrev_b32_e32 v2, 1, v2
	v_readlane_b32 s33, v254, 22
	s_mov_b32 s37, s4
	s_barrier
	v_readlane_b32 s5, v254, 24
	s_branch .LBB0_505

; #define PG8_STAGE(bufoff, gbase, voff) do { _Pragma("unroll") for (int _i = 0; _i < 2; ++_i) \
;         __builtin_amdgcn_global_load_lds((const unsigned*)((const char*)(gbase) + (voff)[_i]), (PG8_LAS unsigned*)(lds + (bufoff) + ldsw + _i * 8192), 16, 0, 0); } while (0)
; #define PG8_WAIT_V(n) asm volatile("s_waitcnt vmcnt(" #n ")" ::: "memory")
; #define PG8_BAR __builtin_amdgcn_s_barrier()
; template <class Epi, class Sched, bool ALIGN_EPI = false, bool SP2 = false, bool NAT = false>
; __device__ __forceinline__ void gemm_phase(PG8_LAS unsigned char* lds, const Gemm g, const Sched& S, const Epi& E) {
;     ...
;     for (int i = 0; i < 2; ++i) { int R, C; stage_rc(tid * 16 + i * 8192, R, C); const int Rb = Epi::PERM ? ((R & ~31) + perm32(R & 31)) : R;
;         voffA[i] = (unsigned)(R * K + C) * 2u; voffB[i] = (unsigned)(Rb * K + C) * 2u; }
;     const size_t kstep = (size_t)(BK * 2);
;     const size_t hstep = (size_t)HALF * K * 2;
;     const size_t tstep = 2 * hstep;
;     const unsigned ldsw = (unsigned)wid * 1024u;
;     const int aoff = lds_byte(wr * 64 + fr, fq * 8), boff = lds_byte(wc * 32 + fr, fq * 8);
;     ...
;     if constexpr (SP2) {
;         PG8_STAGE(PG8_SB(0, 0), cB, voffB); PG8_STAGE(PG8_SB(0, 1), cB + hstep, voffB); PG8_STAGE(PG8_SA(0, 0), cA, voffA); PG8_STAGE(PG8_SA(0, 1), cA + hstep, voffA);
;         if (wr == 1) PG8_BAR;
;         PG8_WAIT_V(2); PG8_BAR;
;         PG8_STAGE(PG8_SB(1, 0), cB + kstep, voffB); PG8_STAGE(PG8_SA(1, 0), cA + kstep, voffA); PG8_STAGE(PG8_SB(1, 1), cB + hstep + kstep, voffB);
;         PG8_WAIT_V(6); PG8_BAR;
.LBB0_526:
	v_readlane_b32 s17, v255, 8
	s_add_u32 s39, s4, s17
	s_addc_u32 s42, s5, 0
	s_lshl_b32 s4, s15, 5
	s_and_b32 s17, s4, 0x60
	s_add_i32 m0, s35, 0x18000
	v_lshl_add_u64 v[10:11], v[10:11], 0, s[92:93]
	s_lshl_b32 s43, s16, 6
	s_lshl_b32 s16, s16, 13
	s_lshl_b32 s15, s17, 7
	global_load_lds_dwordx4 v[10:11], off
	v_lshl_add_u64 v[8:9], v[8:9], 0, s[92:93]
	s_add_i32 m0, s35, 0x1a000
	s_add_i32 s44, s35, 0x8000
	s_add_i32 s45, s35, 0xa000
	global_load_lds_dwordx4 v[8:9], off
	v_lshl_add_u64 v[4:5], v[4:5], 0, s[92:93]
	s_mov_b32 m0, s44
	s_add_u32 s4, s26, 0x40080
	global_load_lds_dwordx4 v[4:5], off
	v_lshl_add_u64 v[4:5], v[6:7], 0, s[92:93]
	s_mov_b32 m0, s45
	s_addc_u32 s5, s27, 0
	global_load_lds_dwordx4 v[4:5], off
	s_add_i32 m0, s35, 0x1c000
	v_lshl_add_u64 v[4:5], s[4:5], 0, v[2:3]
	global_load_lds_dwordx4 v[4:5], off
	v_lshl_add_u64 v[4:5], s[4:5], 0, v[0:1]
	s_add_i32 m0, s35, 0x1e000
	v_and_b32_e32 v170, 15, v12
	global_load_lds_dwordx4 v[4:5], off
	v_bfe_u32 v4, v12, 4, 2
	v_lshlrev_b32_e32 v5, 4, v4
	v_lshl_or_b32 v172, v4, 2, s17
	v_lshlrev_b32_e32 v4, 13, v13
	v_and_b32_e32 v4, 0x7fffc000, v4
	v_lshlrev_b32_e32 v6, 2, v12
	v_lshl_add_u32 v4, v14, 10, v4
	v_lshl_or_b32 v5, v170, 6, v5
	v_and_b32_e32 v6, 32, v6
	v_or_b32_e32 v4, v4, v15
	v_bitop3_b32 v7, v5, s16, v6 bitop3:0xde
	v_bitop3_b32 v171, v5, s15, v6 bitop3:0xde
	v_add_lshl_u32 v4, v4, v16, 1
	v_mov_b32_e32 v5, v3
	s_mov_b64 s[4:5], 0x40080
	v_lshl_add_u64 v[132:133], v[4:5], 0, s[4:5]
	v_lshlrev_b32_e32 v4, 13, v18
	v_and_b32_e32 v4, 0x7fffc000, v4
	v_lshl_add_u32 v4, v17, 10, v4
	v_or_b32_e32 v4, v4, v19
	s_waitcnt vmcnt(8)
	s_barrier
	s_waitcnt vmcnt(6)
	v_add_lshl_u32 v4, v4, v20, 1
	s_cmpk_lt_u32 s14, 0x100
	v_lshl_add_u64 v[134:135], v[4:5], 0, s[4:5]
	v_readlane_b32 s4, v254, 46
	s_cselect_b64 s[14:15], -1, 0
	s_mov_b32 s46, 0
	v_add_u32_e32 v173, 0, v7
	v_readlane_b32 s47, v254, 45
	s_mov_b32 s48, s4
	s_barrier
	v_readlane_b32 s5, v254, 47
	s_branch .LBB0_529

; #define PG8_STAGE(bufoff, gbase, voff) do { _Pragma("unroll") for (int _i = 0; _i < 2; ++_i) \
;         __builtin_amdgcn_global_load_lds((const unsigned*)((const char*)(gbase) + (voff)[_i]), (PG8_LAS unsigned*)(lds + (bufoff) + ldsw + _i * 8192), 16, 0, 0); } while (0)
; #define PG8_WAIT_V(n) asm volatile("s_waitcnt vmcnt(" #n ")" ::: "memory")
; #define PG8_BAR __builtin_amdgcn_s_barrier()
; template <class Epi, class Sched, bool ALIGN_EPI = false, bool SP2 = false, bool NAT = false>
; __device__ __forceinline__ void gemm_phase(PG8_LAS unsigned char* lds, const Gemm g, const Sched& S, const Epi& E) {
;     ...
;     for (int i = 0; i < 2; ++i) { int R, C; stage_rc(tid * 16 + i * 8192, R, C); const int Rb = Epi::PERM ? ((R & ~31) + perm32(R & 31)) : R;
;         voffA[i] = (unsigned)(R * K + C) * 2u; voffB[i] = (unsigned)(Rb * K + C) * 2u; }
;     const size_t kstep = (size_t)(BK * 2);
;     const size_t hstep = (size_t)HALF * K * 2;
;     const size_t tstep = 2 * hstep;
;     const unsigned ldsw = (unsigned)wid * 1024u;
;     const int aoff = lds_byte(wr * 64 + fr, fq * 8), boff = lds_byte(wc * 32 + fr, fq * 8);
;     ...
;     if constexpr (SP2) {
;         PG8_STAGE(PG8_SB(0, 0), cB, voffB); PG8_STAGE(PG8_SB(0, 1), cB + hstep, voffB); PG8_STAGE(PG8_SA(0, 0), cA, voffA); PG8_STAGE(PG8_SA(0, 1), cA + hstep, voffA);
;         if (wr == 1) PG8_BAR;
;         PG8_WAIT_V(2); PG8_BAR;
;         PG8_STAGE(PG8_SB(1, 0), cB + kstep, voffB); PG8_STAGE(PG8_SA(1, 0), cA + kstep, voffA); PG8_STAGE(PG8_SB(1, 1), cB + hstep + kstep, voffB);
;         PG8_WAIT_V(6); PG8_BAR;
.LBB0_669:
	v_readlane_b32 s28, v255, 15
	v_readlane_b32 s29, v255, 16
	s_waitcnt lgkmcnt(0)
	s_add_u32 s4, s4, s28
	s_addc_u32 s5, s5, s29
	s_and_b32 s30, s27, 3
	s_add_i32 m0, s63, 0x18000
	v_lshl_add_u64 v[10:11], v[10:11], 0, s[92:93]
	s_lshl_b32 s67, s26, 6
	s_lshl_b32 s28, s26, 13
	s_lshl_b32 s29, s30, 12
	global_load_lds_dwordx4 v[10:11], off
	v_lshl_add_u64 v[8:9], v[8:9], 0, s[92:93]
	s_add_i32 m0, s63, 0x1a000
	s_add_i32 s68, s63, 0x8000
	s_add_i32 s69, s63, 0xa000
	global_load_lds_dwordx4 v[8:9], off
	v_lshl_add_u64 v[4:5], v[4:5], 0, s[92:93]
	s_mov_b32 m0, s68
	s_add_u32 s26, s50, 0x40080
	global_load_lds_dwordx4 v[4:5], off
	v_lshl_add_u64 v[4:5], v[6:7], 0, s[92:93]
	s_mov_b32 m0, s69
	s_addc_u32 s27, s51, 0
	global_load_lds_dwordx4 v[4:5], off
	s_add_i32 m0, s63, 0x1c000
	v_lshl_add_u64 v[4:5], s[26:27], 0, v[132:133]
	global_load_lds_dwordx4 v[4:5], off
	v_lshl_add_u64 v[4:5], s[26:27], 0, v[0:1]
	s_add_i32 m0, s63, 0x1e000
	v_and_b32_e32 v137, 15, v15
	global_load_lds_dwordx4 v[4:5], off
	v_bfe_u32 v4, v15, 4, 2
	v_lshlrev_b32_e32 v2, 4, v4
	v_lshlrev_b32_e32 v6, 2, v15
	s_cmpk_lt_u32 s2, 0x100
	v_lshl_or_b32 v5, v137, 6, v2
	v_and_b32_e32 v6, 32, v6
	s_cselect_b64 s[26:27], -1, 0
	s_cmp_lg_u32 s30, 0
	v_bitop3_b32 v7, v5, s28, v6 bitop3:0xde
	v_bitop3_b32 v165, v5, s29, v6 bitop3:0xde
	v_lshlrev_b32_e32 v166, 2, v4
	s_cselect_b64 s[28:29], -1, 0
	s_cmp_eq_u32 s30, 1
	v_lshl_add_u64 v[154:155], s[4:5], 0, v[2:3]
	v_lshlrev_b32_e32 v2, 14, v12
	v_lshl_or_b32 v136, s30, 5, v166
	s_cselect_b64 s[30:31], -1, 0
	v_cmp_gt_u32_e32 vcc, 2, v4
	v_and_b32_e32 v2, 0xffff8000, v2
	v_lshlrev_b32_e32 v134, 3, v4
	s_waitcnt vmcnt(8)
	s_barrier
	s_waitcnt vmcnt(6)
	s_barrier
	s_and_b64 s[30:31], s[30:31], vcc
	s_load_dwordx2 s[4:5], s[0:1], 0x120
	v_lshl_add_u32 v2, v13, 11, v2
	v_and_b32_e32 v4, 1, v12
	s_add_u32 s34, s16, 0x200
	v_lshl_or_b32 v2, v4, 6, v2
	s_addc_u32 s35, s17, 0
	v_lshl_add_u32 v158, v14, 1, v2
	v_lshlrev_b32_e32 v2, 14, v16
	s_add_u32 s36, s18, 0x100
	v_and_b32_e32 v2, 0xffff8000, v2
	s_addc_u32 s37, s19, 0
	v_mov_b32_e32 v135, v3
	v_lshl_add_u32 v2, v17, 11, v2
	v_and_b32_e32 v4, 1, v16
	s_add_u32 s38, s16, 0x100
	s_waitcnt lgkmcnt(0)
	v_lshl_add_u64 v[156:157], s[4:5], 0, v[134:135]
	v_lshl_or_b32 v2, v4, 6, v2
	v_readlane_b32 s4, v254, 52
	s_mov_b32 s70, 0
	v_or_b32_e32 v167, 1, v166
	v_or_b32_e32 v168, 2, v166
	v_or_b32_e32 v169, 3, v166
	s_addc_u32 s39, s17, 0
	v_mov_b32_e32 v159, v3
	v_lshl_add_u32 v160, v18, 1, v2
	v_mov_b32_e32 v161, v3
	v_add_u32_e32 v135, 0, v7
	v_readlane_b32 s71, v254, 31
	s_mov_b32 s2, s4
	v_readlane_b32 s5, v254, 53
	s_branch .LBB0_672

; #define PG8_STAGE(bufoff, gbase, voff) do { _Pragma("unroll") for (int _i = 0; _i < 2; ++_i) \
;         __builtin_amdgcn_global_load_lds((const unsigned*)((const char*)(gbase) + (voff)[_i]), (PG8_LAS unsigned*)(lds + (bufoff) + ldsw + _i * 8192), 16, 0, 0); } while (0)
; #define PG8_WAIT_V(n) asm volatile("s_waitcnt vmcnt(" #n ")" ::: "memory")
; #define PG8_BAR __builtin_amdgcn_s_barrier()
; template <class Epi, class Sched, bool ALIGN_EPI = false, bool SP2 = false, bool NAT = false>
; __device__ __forceinline__ void gemm_phase(PG8_LAS unsigned char* lds, const Gemm g, const Sched& S, const Epi& E) {
;     ...
;     for (int i = 0; i < 2; ++i) { int R, C; stage_rc(tid * 16 + i * 8192, R, C); const int Rb = Epi::PERM ? ((R & ~31) + perm32(R & 31)) : R;
;         voffA[i] = (unsigned)(R * K + C) * 2u; voffB[i] = (unsigned)(Rb * K + C) * 2u; }
;     const size_t kstep = (size_t)(BK * 2);
;     const size_t hstep = (size_t)HALF * K * 2;
;     const size_t tstep = 2 * hstep;
;     const unsigned ldsw = (unsigned)wid * 1024u;
;     const int aoff = lds_byte(wr * 64 + fr, fq * 8), boff = lds_byte(wc * 32 + fr, fq * 8);
;     ...
;     if constexpr (SP2) {
;         PG8_STAGE(PG8_SB(0, 0), cB, voffB); PG8_STAGE(PG8_SB(0, 1), cB + hstep, voffB); PG8_STAGE(PG8_SA(0, 0), cA, voffA); PG8_STAGE(PG8_SA(0, 1), cA + hstep, voffA);
;         if (wr == 1) PG8_BAR;
;         PG8_WAIT_V(2); PG8_BAR;
;         PG8_STAGE(PG8_SB(1, 0), cB + kstep, voffB); PG8_STAGE(PG8_SA(1, 0), cA + kstep, voffA); PG8_STAGE(PG8_SB(1, 1), cB + hstep + kstep, voffB);
;         PG8_WAIT_V(6); PG8_BAR;
.LBB0_731:
	v_mov_b32_e32 v133, v3
	v_lshl_add_u64 v[10:11], s[24:25], 0, v[132:133]
	v_mov_b32_e32 v1, v3
	s_lshl_b32 s5, s5, 5
	v_lshl_add_u64 v[12:13], s[24:25], 0, v[0:1]
	s_and_b32 s38, s5, 0x60
	s_add_i32 m0, s33, 0x18000
	v_lshl_add_u64 v[10:11], v[10:11], 0, s[92:93]
	v_lshl_add_u64 v[14:15], s[26:27], 0, v[132:133]
	s_lshl_b32 s37, s14, 6
	s_lshl_b32 s16, s14, 13
	s_lshl_b32 s17, s38, 7
	global_load_lds_dwordx4 v[10:11], off
	v_lshl_add_u64 v[10:11], v[12:13], 0, s[92:93]
	s_add_i32 m0, s33, 0x1a000
	s_add_i32 s39, s33, 0x8000
	s_add_i32 s42, s33, 0xa000
	v_lshl_add_u64 v[16:17], s[26:27], 0, v[0:1]
	global_load_lds_dwordx4 v[10:11], off
	v_lshl_add_u64 v[10:11], v[14:15], 0, s[92:93]
	s_mov_b32 m0, s39
	s_add_u32 s14, s24, 0x40080
	global_load_lds_dwordx4 v[10:11], off
	v_lshl_add_u64 v[10:11], v[16:17], 0, s[92:93]
	s_mov_b32 m0, s42
	s_addc_u32 s15, s25, 0
	global_load_lds_dwordx4 v[10:11], off
	s_add_i32 m0, s33, 0x1c000
	v_lshl_add_u64 v[10:11], s[14:15], 0, v[132:133]
	global_load_lds_dwordx4 v[10:11], off
	v_lshl_add_u64 v[10:11], s[14:15], 0, v[0:1]
	s_add_i32 m0, s33, 0x1e000
	s_cmpk_lt_u32 s4, 0x100
	global_load_lds_dwordx4 v[10:11], off
	v_bfe_u32 v11, v2, 4, 2
	v_and_b32_e32 v10, 15, v2
	v_lshlrev_b32_e32 v12, 4, v11
	v_lshlrev_b32_e32 v2, 2, v2
	v_lshl_or_b32 v12, v10, 6, v12
	v_and_b32_e32 v2, 32, v2
	v_bitop3_b32 v13, v12, s16, v2 bitop3:0xde
	v_bitop3_b32 v135, v12, s17, v2 bitop3:0xde
	v_and_or_b32 v2, s5, 32, v10
	v_lshlrev_b32_e32 v10, 14, v4
	v_and_b32_e32 v10, 0xffff8000, v10
	v_lshl_add_u32 v5, v5, 11, v10
	v_and_b32_e32 v4, 1, v4
	v_lshl_or_b32 v4, v4, 6, v5
	v_lshl_add_u32 v136, v6, 1, v4
	v_lshlrev_b32_e32 v4, 14, v7
	v_and_b32_e32 v4, 0xffff8000, v4
	s_waitcnt vmcnt(8)
	s_barrier
	s_waitcnt vmcnt(6)
	v_lshl_add_u32 v4, v8, 11, v4
	v_and_b32_e32 v5, 1, v7
	v_lshlrev_b32_e32 v2, 6, v2
	v_lshl_or_b32 v4, v5, 6, v4
	v_readlane_b32 s4, v254, 46
	s_cselect_b64 s[14:15], -1, 0
	v_lshlrev_b32_e32 v134, 2, v11
	v_mov_b32_e32 v137, v3
	v_lshl_add_u32 v154, v9, 1, v4
	v_mov_b32_e32 v155, v3
	s_mov_b32 s43, 0
	v_add_u32_e32 v156, 0, v13
	v_lshlrev_b32_e32 v2, 1, v2
	v_readlane_b32 s44, v254, 45
	s_mov_b32 s45, s4
	s_barrier
	v_readlane_b32 s5, v254, 47
	s_branch .LBB0_734
